# FFN-up GEMM: tile-top vmcnt(0) relaxed to vmcnt(4) (only the four trailing epilogue stores can be outstanding there)
# baseline (speedup 1.0000x reference)
.LBB0_1329:
	s_ashr_i32 s67, s66, 31
	s_lshl_b64 s[10:11], s[66:67], 19
	v_readlane_b32 s12, v254, 62
	s_add_u32 s70, s12, s10
	v_readlane_b32 s10, v255, 0
	s_addc_u32 s71, s10, s11
	s_and_b64 s[10:11], s[4:5], exec
	s_cselect_b32 s12, s71, s7
	s_cselect_b32 s13, s70, s6
	s_ashr_i32 s65, s64, 31
	s_lshl_b64 s[10:11], s[64:65], 19
	v_readlane_b32 s14, v255, 1
	s_add_u32 s20, s14, s10
	v_readlane_b32 s10, v255, 4
	s_addc_u32 s21, s10, s11
	s_and_b64 s[10:11], s[4:5], exec
	s_cselect_b32 s14, s21, s9
	s_cselect_b32 s15, s20, s8
	s_add_u32 s6, s6, 0x40080
	s_addc_u32 s7, s7, 0
	s_add_u32 s17, s8, 0x100
	v_mov_b32_e32 v130, 0
	s_addc_u32 s18, s9, 0
	s_mov_b32 s19, -2
	v_mov_b32_e32 v131, v130
	v_mov_b32_e32 v132, v130
	v_mov_b32_e32 v133, v130
	v_mov_b32_e32 v62, v130
	v_mov_b32_e32 v63, v130
	v_mov_b32_e32 v64, v130
	v_mov_b32_e32 v65, v130
	v_mov_b32_e32 v2, v130
	v_mov_b32_e32 v3, v130
	v_mov_b32_e32 v4, v130
	v_mov_b32_e32 v5, v130
	v_mov_b32_e32 v42, v130
	v_mov_b32_e32 v43, v130
	v_mov_b32_e32 v44, v130
	v_mov_b32_e32 v45, v130
	v_mov_b32_e32 v6, v130
	v_mov_b32_e32 v7, v130
	v_mov_b32_e32 v8, v130
	v_mov_b32_e32 v9, v130
	v_mov_b32_e32 v46, v130
	v_mov_b32_e32 v47, v130
	v_mov_b32_e32 v48, v130
	v_mov_b32_e32 v49, v130
	v_mov_b32_e32 v106, v130
	v_mov_b32_e32 v107, v130
	v_mov_b32_e32 v108, v130
	v_mov_b32_e32 v109, v130
	v_mov_b32_e32 v114, v130
	v_mov_b32_e32 v115, v130
	v_mov_b32_e32 v116, v130
	v_mov_b32_e32 v117, v130
	v_mov_b32_e32 v134, v130
	v_mov_b32_e32 v135, v130
	v_mov_b32_e32 v136, v130
	v_mov_b32_e32 v137, v130
	v_mov_b32_e32 v58, v130
	v_mov_b32_e32 v59, v130
	v_mov_b32_e32 v60, v130
	v_mov_b32_e32 v61, v130
	v_mov_b32_e32 v10, v130
	v_mov_b32_e32 v11, v130
	v_mov_b32_e32 v12, v130
	v_mov_b32_e32 v13, v130
	v_mov_b32_e32 v50, v130
	v_mov_b32_e32 v51, v130
	v_mov_b32_e32 v52, v130
	v_mov_b32_e32 v53, v130
	v_mov_b32_e32 v14, v130
	v_mov_b32_e32 v15, v130
	v_mov_b32_e32 v16, v130
	v_mov_b32_e32 v17, v130
	v_mov_b32_e32 v54, v130
	v_mov_b32_e32 v55, v130
	v_mov_b32_e32 v56, v130
	v_mov_b32_e32 v57, v130
	v_mov_b32_e32 v122, v130
	v_mov_b32_e32 v123, v130
	v_mov_b32_e32 v124, v130
	v_mov_b32_e32 v125, v130
	v_mov_b32_e32 v126, v130
	v_mov_b32_e32 v127, v130
	v_mov_b32_e32 v128, v130
	v_mov_b32_e32 v129, v130
	v_mov_b32_e32 v98, v130
	v_mov_b32_e32 v99, v130
	v_mov_b32_e32 v100, v130
	v_mov_b32_e32 v101, v130
	v_mov_b32_e32 v102, v130
	v_mov_b32_e32 v103, v130
	v_mov_b32_e32 v104, v130
	v_mov_b32_e32 v105, v130
	v_mov_b32_e32 v18, v130
	v_mov_b32_e32 v19, v130
	v_mov_b32_e32 v20, v130
	v_mov_b32_e32 v21, v130
	v_mov_b32_e32 v66, v130
	v_mov_b32_e32 v67, v130
	v_mov_b32_e32 v68, v130
	v_mov_b32_e32 v69, v130
	v_mov_b32_e32 v22, v130
	v_mov_b32_e32 v23, v130
	v_mov_b32_e32 v24, v130
	v_mov_b32_e32 v25, v130
	v_mov_b32_e32 v70, v130
	v_mov_b32_e32 v71, v130
	v_mov_b32_e32 v72, v130
	v_mov_b32_e32 v73, v130
	v_mov_b32_e32 v138, v130
	v_mov_b32_e32 v139, v130
	v_mov_b32_e32 v140, v130
	v_mov_b32_e32 v141, v130
	v_mov_b32_e32 v82, v130
	v_mov_b32_e32 v83, v130
	v_mov_b32_e32 v84, v130
	v_mov_b32_e32 v85, v130
	v_mov_b32_e32 v110, v130
	v_mov_b32_e32 v111, v130
	v_mov_b32_e32 v112, v130
	v_mov_b32_e32 v113, v130
	v_mov_b32_e32 v118, v130
	v_mov_b32_e32 v119, v130
	v_mov_b32_e32 v120, v130
	v_mov_b32_e32 v121, v130
	v_mov_b32_e32 v26, v130
	v_mov_b32_e32 v27, v130
	s_waitcnt vmcnt(4)
	v_mov_b32_e32 v28, v130
	v_mov_b32_e32 v29, v130
	v_mov_b32_e32 v74, v130
	v_mov_b32_e32 v75, v130
	v_mov_b32_e32 v76, v130
	v_mov_b32_e32 v77, v130
	v_mov_b32_e32 v30, v130
	v_mov_b32_e32 v31, v130
	v_mov_b32_e32 v32, v130
	v_mov_b32_e32 v33, v130
	v_mov_b32_e32 v78, v130
	v_mov_b32_e32 v79, v130
	v_mov_b32_e32 v80, v130
	v_mov_b32_e32 v81, v130
	v_mov_b32_e32 v142, v130
	v_mov_b32_e32 v143, v130
	v_mov_b32_e32 v144, v130
	v_mov_b32_e32 v145, v130
	v_mov_b32_e32 v94, v130
	v_mov_b32_e32 v95, v130
	v_mov_b32_e32 v96, v130
	v_mov_b32_e32 v97, v130
